# RWKV prompt-scan chunk loop: vmcnt(0) drains relaxed to vmcnt(1) so the per-chunk Y store no longer stalls the serial scan
# speedup vs baseline: 1.0263x; 1.0111x over previous
; DI void scan_chunk(const float* buf, f32x4& S, int w, int rw, int kg, float& ys) {
;   float yp[16];
; #pragma unroll
;   for (int s = 0; s < 16; ++s) {
;     const float* b = buf + s * 64 + kg * 4;
;     f32x4 d = *(const f32x4*)(b), n = *(const f32x4*)(b + 1024), a = *(const f32x4*)(b + 2048), k = *(const f32x4*)(b + 3072),
;           r = *(const f32x4*)(b + 4096);
;     float vv = buf[5120 + s * 16 + w * 4 + rw];
;     float pp = S[0] * n[0];
;     pp = fmaf(S[1], n[1], pp); pp = fmaf(S[2], n[2], pp); pp = fmaf(S[3], n[3], pp);
;     float sa = row_allreduce(pp);
; #pragma unroll
;     for (int e = 0; e < 4; ++e) S[e] = fmaf(sa, a[e], fmaf(S[e], d[e], vv * k[e]));
;     float y = S[0] * r[0];
;     y = fmaf(S[1], r[1], y); y = fmaf(S[2], r[2], y); y = fmaf(S[3], r[3], y);
;     yp[s] = y;
;   }
; DI void scan_job(const int tid_, const Params& p, int l, int job, char* s0, char* s1, char* s2) {
;     ...
;   for (int c = 0; c < nchunks; c += 2) {
;     if (c + 2 < nchunks) scan_gload(tid_, B, p, tok0 + (c + 2) * 16, h, rg);
;     float ys = 0.f;
;     scan_chunk(buf0, S, w, rw, kg, ys);
;     Y[(size_t)(tok0 + c * 16 + kg) * 512 + h * 64 + row] = ys;
.LBB0_184:
	s_add_i32 s21, s20, -1
	s_cmp_lt_u32 s21, s39
	s_cselect_b64 s[30:31], -1, 0
	s_cmp_ge_u32 s21, s39
	s_cbranch_scc1 .LBB0_186
	s_waitcnt vmcnt(1)
	v_add3_u32 v14, v48, s38, 32
	v_ashrrev_i32_e32 v15, 31, v14
	v_lshlrev_b64 v[16:17], 11, v[14:15]
	v_lshlrev_b64 v[14:15], 10, v[14:15]
	v_lshl_add_u64 v[16:17], v[38:39], 0, v[16:17]
	v_lshl_add_u64 v[18:19], v[40:41], 0, v[14:15]
	v_add3_u32 v0, v49, s38, 32
	flat_load_dwordx4 v[14:17], v[16:17]
	s_nop 0
	flat_load_ushort v61, v[18:19]
	v_lshlrev_b64 v[18:19], 10, v[0:1]
	v_lshl_or_b32 v18, v42, 1, v18
	v_lshl_add_u64 v[20:21], v[32:33], 0, v[18:19]
	v_lshl_add_u64 v[22:23], v[34:35], 0, v[18:19]
	flat_load_dwordx4 v[18:21], v[20:21]
	s_nop 0
	flat_load_dwordx4 v[22:25], v[22:23]
.LBB0_186:
	ds_read_b128 v[62:65], v51 offset:4096
	v_add_u32_e32 v46, 0x5000, v55
	ds_read_b128 v[66:69], v51 offset:4352
	ds_read2_b32 v[130:131], v46 offset1:16
	s_add_i32 s28, s20, -2
	s_cmp_lt_u32 s28, s39
	s_waitcnt lgkmcnt(0)
	v_mul_f32_e32 v0, v26, v62
	v_fmac_f32_e32 v0, v27, v63
	v_fmac_f32_e32 v0, v28, v64
	v_fmac_f32_e32 v0, v29, v65
	ds_read_b128 v[62:65], v51
	ds_read_b128 v[70:73], v51 offset:256
	ds_read_b128 v[74:77], v51 offset:8192
	ds_read_b128 v[78:81], v51 offset:8448
	ds_read_b128 v[82:85], v51 offset:12288
	ds_read_b128 v[86:89], v51 offset:12544
	ds_read_b128 v[90:93], v51 offset:16384
	ds_read_b128 v[94:97], v51 offset:16640
	ds_read2_b32 v[158:159], v46 offset0:32 offset1:48
	ds_read_b128 v[98:101], v51 offset:512
	ds_read_b128 v[102:105], v51 offset:768
	ds_read_b128 v[106:109], v51 offset:4608
	ds_read_b128 v[110:113], v51 offset:4864
	ds_read_b128 v[114:117], v51 offset:8704
	ds_read_b128 v[118:121], v51 offset:8960
	ds_read_b128 v[122:125], v51 offset:12800
	ds_read_b128 v[126:129], v51 offset:13056
	ds_read_b128 v[138:141], v51 offset:16896
	ds_read_b128 v[142:145], v51 offset:17152
	ds_read_b128 v[146:149], v51 offset:1024
	ds_read_b128 v[150:153], v51 offset:5120
	ds_read_b128 v[154:157], v51 offset:13312
	ds_read2_b32 v[44:45], v46 offset0:64 offset1:80
	v_add_f32_dpp v0, v0, v0 row_ror:8 row_mask:0xf bank_mask:0xf bound_ctrl:1
	s_waitcnt lgkmcnt(0)
	v_pk_mul_f32 v[82:83], v[82:83], v[130:131] op_sel_hi:[1,0]
	v_pk_mul_f32 v[84:85], v[84:85], v[130:131] op_sel_hi:[1,0]
	v_add_f32_dpp v0, v0, v0 row_ror:4 row_mask:0xf bank_mask:0xf bound_ctrl:1
	v_pk_fma_f32 v[26:27], v[26:27], v[62:63], v[82:83]
	v_pk_fma_f32 v[28:29], v[28:29], v[64:65], v[84:85]
	v_add_f32_dpp v0, v0, v0 row_ror:2 row_mask:0xf bank_mask:0xf bound_ctrl:1
	v_mov_b32_e32 v84, v159
	s_cselect_b64 s[8:9], -1, 0
	v_add_f32_dpp v0, v0, v0 row_ror:1 row_mask:0xf bank_mask:0xf bound_ctrl:1
	v_pk_fma_f32 v[26:27], v[0:1], v[74:75], v[26:27] op_sel_hi:[0,1,1]
	v_mul_f32_e32 v47, v66, v26
	v_pk_fma_f32 v[64:65], v[0:1], v[76:77], v[28:29] op_sel_hi:[0,1,1]
	v_fmac_f32_e32 v47, v27, v67
	v_fmac_f32_e32 v47, v64, v68
	v_fmac_f32_e32 v47, v65, v69
	v_mov_b32_e32 v28, v131
	v_mul_f32_e32 v0, v90, v26
	v_add_f32_dpp v47, v47, v47 row_ror:8 row_mask:0xf bank_mask:0xf bound_ctrl:1
	v_pk_mul_f32 v[76:77], v[88:89], v[28:29] op_sel_hi:[1,0]
	v_fmac_f32_e32 v0, v27, v91
	v_add_f32_dpp v47, v47, v47 row_ror:4 row_mask:0xf bank_mask:0xf bound_ctrl:1
	v_pk_mul_f32 v[28:29], v[86:87], v[28:29] op_sel_hi:[1,0]
	v_pk_fma_f32 v[72:73], v[64:65], v[72:73], v[76:77]
	v_add_f32_dpp v47, v47, v47 row_ror:2 row_mask:0xf bank_mask:0xf bound_ctrl:1
	v_pk_fma_f32 v[62:63], v[26:27], v[70:71], v[28:29]
	v_fmac_f32_e32 v0, v64, v92
	v_add_f32_dpp v64, v47, v47 row_ror:1 row_mask:0xf bank_mask:0xf bound_ctrl:1
	v_pk_fma_f32 v[62:63], v[64:65], v[78:79], v[62:63] op_sel_hi:[0,1,1]
	v_mul_f32_e32 v68, v106, v62
	v_fmac_f32_e32 v0, v65, v93
	v_pk_fma_f32 v[64:65], v[64:65], v[80:81], v[72:73] op_sel_hi:[0,1,1]
	v_fmac_f32_e32 v68, v63, v107
	v_fmac_f32_e32 v68, v64, v108
	v_fmac_f32_e32 v68, v65, v109
	v_pk_mul_f32 v[66:67], v[122:123], v[158:159] op_sel_hi:[1,0]
	v_mul_f32_e32 v47, v94, v62
	v_add_f32_dpp v68, v68, v68 row_ror:8 row_mask:0xf bank_mask:0xf bound_ctrl:1
	v_pk_mul_f32 v[76:77], v[124:125], v[158:159] op_sel_hi:[1,0]
	v_fmac_f32_e32 v47, v63, v95
	v_add_f32_dpp v68, v68, v68 row_ror:4 row_mask:0xf bank_mask:0xf bound_ctrl:1
	v_pk_fma_f32 v[62:63], v[62:63], v[98:99], v[66:67]
	v_fmac_f32_e32 v47, v64, v96
	v_add_f32_dpp v68, v68, v68 row_ror:2 row_mask:0xf bank_mask:0xf bound_ctrl:1
	v_fmac_f32_e32 v47, v65, v97
	v_pk_mul_f32 v[70:71], v[126:127], v[84:85] op_sel_hi:[1,0]
	v_add_f32_dpp v68, v68, v68 row_ror:1 row_mask:0xf bank_mask:0xf bound_ctrl:1
	v_pk_fma_f32 v[66:67], v[68:69], v[114:115], v[62:63] op_sel_hi:[0,1,1]
	v_pk_fma_f32 v[62:63], v[64:65], v[100:101], v[76:77]
	v_pk_mul_f32 v[88:89], v[128:129], v[84:85] op_sel_hi:[1,0]
	v_pk_fma_f32 v[64:65], v[68:69], v[116:117], v[62:63] op_sel_hi:[0,1,1]
	v_mul_f32_e32 v63, v110, v66
	v_fmac_f32_e32 v63, v67, v111
	v_fmac_f32_e32 v63, v64, v112
	v_fmac_f32_e32 v63, v65, v113
	v_mul_f32_e32 v62, v138, v66
	v_fmac_f32_e32 v62, v67, v139
	v_add_f32_dpp v63, v63, v63 row_ror:8 row_mask:0xf bank_mask:0xf bound_ctrl:1
	v_fmac_f32_e32 v62, v64, v140
	v_pk_fma_f32 v[66:67], v[66:67], v[102:103], v[70:71]
	v_add_f32_dpp v63, v63, v63 row_ror:4 row_mask:0xf bank_mask:0xf bound_ctrl:1
	v_fmac_f32_e32 v62, v65, v141
	v_pk_fma_f32 v[64:65], v[64:65], v[104:105], v[88:89]
	v_add_f32_dpp v63, v63, v63 row_ror:2 row_mask:0xf bank_mask:0xf bound_ctrl:1
	v_pk_mul_f32 v[74:75], v[154:155], v[44:45] op_sel_hi:[1,0]
	ds_read_b128 v[26:29], v51 offset:13568
	v_add_f32_dpp v68, v63, v63 row_ror:1 row_mask:0xf bank_mask:0xf bound_ctrl:1
	v_pk_fma_f32 v[72:73], v[68:69], v[118:119], v[66:67] op_sel_hi:[0,1,1]
; DI void scan_chunk(const float* buf, f32x4& S, int w, int rw, int kg, float& ys) {
;   float yp[16];
; #pragma unroll
;   for (int s = 0; s < 16; ++s) {
;     const float* b = buf + s * 64 + kg * 4;
;     f32x4 d = *(const f32x4*)(b), n = *(const f32x4*)(b + 1024), a = *(const f32x4*)(b + 2048), k = *(const f32x4*)(b + 3072),
;           r = *(const f32x4*)(b + 4096);
;     float vv = buf[5120 + s * 16 + w * 4 + rw];
;     float pp = S[0] * n[0];
;     pp = fmaf(S[1], n[1], pp); pp = fmaf(S[2], n[2], pp); pp = fmaf(S[3], n[3], pp);
;     float sa = row_allreduce(pp);
; #pragma unroll
;     for (int e = 0; e < 4; ++e) S[e] = fmaf(sa, a[e], fmaf(S[e], d[e], vv * k[e]));
;     float y = S[0] * r[0];
;     y = fmaf(S[1], r[1], y); y = fmaf(S[2], r[2], y); y = fmaf(S[3], r[3], y);
;     yp[s] = y;
;   }
	v_pk_fma_f32 v[76:77], v[68:69], v[120:121], v[64:65] op_sel_hi:[0,1,1]
	v_mul_f32_e32 v68, v150, v72
	v_fmac_f32_e32 v68, v73, v151
	v_fmac_f32_e32 v68, v76, v152
	v_fmac_f32_e32 v68, v77, v153
	v_mul_f32_e32 v63, v142, v72
	ds_read_b128 v[64:67], v51 offset:5376
	v_add_f32_dpp v68, v68, v68 row_ror:8 row_mask:0xf bank_mask:0xf bound_ctrl:1
	v_fmac_f32_e32 v63, v73, v143
	v_fmac_f32_e32 v63, v76, v144
	v_add_f32_dpp v68, v68, v68 row_ror:4 row_mask:0xf bank_mask:0xf bound_ctrl:1
	v_pk_fma_f32 v[188:189], v[72:73], v[146:147], v[74:75]
	v_pk_mul_f32 v[72:73], v[156:157], v[44:45] op_sel_hi:[1,0]
	v_add_f32_dpp v68, v68, v68 row_ror:2 row_mask:0xf bank_mask:0xf bound_ctrl:1
	v_fmac_f32_e32 v63, v77, v145
	v_pk_fma_f32 v[190:191], v[76:77], v[148:149], v[72:73]
	v_add_f32_dpp v186, v68, v68 row_ror:1 row_mask:0xf bank_mask:0xf bound_ctrl:1
	ds_read_b128 v[68:71], v51 offset:1280
	ds_read_b128 v[72:75], v51 offset:9216
	ds_read_b128 v[76:79], v51 offset:9472
	ds_read_b128 v[80:83], v51 offset:17408
	ds_read_b128 v[84:87], v51 offset:17664
	ds_read2_b32 v[192:193], v46 offset0:96 offset1:112
	ds_read_b128 v[88:91], v51 offset:1536
	ds_read_b128 v[92:95], v51 offset:1792
	ds_read_b128 v[96:99], v51 offset:5632
	ds_read_b128 v[100:103], v51 offset:5888
	ds_read_b128 v[104:107], v51 offset:9728
	ds_read_b128 v[108:111], v51 offset:9984
	ds_read_b128 v[112:115], v51 offset:13824
	ds_read_b128 v[116:119], v51 offset:14080
	ds_read_b128 v[120:123], v51 offset:17920
	ds_read_b128 v[124:127], v51 offset:18176
	ds_read2_b32 v[194:195], v46 offset0:128 offset1:144
	ds_read_b128 v[128:131], v51 offset:2048
	ds_read_b128 v[138:141], v51 offset:2304
	ds_read_b128 v[142:145], v51 offset:6144
	ds_read_b128 v[146:149], v51 offset:6400
	ds_read_b128 v[150:153], v51 offset:10240
	ds_read_b128 v[154:157], v51 offset:10496
	ds_read_b128 v[158:161], v51 offset:14336
	ds_read_b128 v[162:165], v51 offset:14592
	ds_read_b128 v[172:175], v51 offset:18432
	ds_read_b128 v[182:185], v51 offset:18688
	s_waitcnt lgkmcnt(0)
	v_pk_fma_f32 v[72:73], v[186:187], v[72:73], v[188:189] op_sel_hi:[0,1,1]
	v_mul_f32_e32 v181, v64, v72
	v_fmac_f32_e32 v181, v73, v65
	v_pk_fma_f32 v[74:75], v[186:187], v[74:75], v[190:191] op_sel_hi:[0,1,1]
	v_fmac_f32_e32 v181, v74, v66
	v_fmac_f32_e32 v181, v75, v67
	v_mov_b32_e32 v44, v45
	v_pk_mul_f32 v[26:27], v[26:27], v[44:45] op_sel_hi:[1,0]
	v_add_f32_dpp v66, v181, v181 row_ror:8 row_mask:0xf bank_mask:0xf bound_ctrl:1
	v_pk_fma_f32 v[26:27], v[72:73], v[68:69], v[26:27]
	v_pk_mul_f32 v[28:29], v[28:29], v[44:45] op_sel_hi:[1,0]
	v_add_f32_dpp v66, v66, v66 row_ror:4 row_mask:0xf bank_mask:0xf bound_ctrl:1
	v_pk_fma_f32 v[28:29], v[74:75], v[70:71], v[28:29]
	v_pk_mul_f32 v[64:65], v[112:113], v[192:193] op_sel_hi:[1,0]
	v_add_f32_dpp v66, v66, v66 row_ror:2 row_mask:0xf bank_mask:0xf bound_ctrl:1
	v_pk_mul_f32 v[44:45], v[114:115], v[192:193] op_sel_hi:[1,0]
	v_mul_f32_e32 v135, v80, v72
	v_add_f32_dpp v66, v66, v66 row_ror:1 row_mask:0xf bank_mask:0xf bound_ctrl:1
	v_pk_fma_f32 v[26:27], v[66:67], v[76:77], v[26:27] op_sel_hi:[0,1,1]
	v_pk_fma_f32 v[28:29], v[66:67], v[78:79], v[28:29] op_sel_hi:[0,1,1]
	v_mul_f32_e32 v66, v96, v26
	v_fmac_f32_e32 v66, v27, v97
	v_fmac_f32_e32 v66, v28, v98
	v_fmac_f32_e32 v66, v29, v99
	v_mul_f32_e32 v181, v84, v26
	v_fmac_f32_e32 v181, v27, v85
	v_add_f32_dpp v66, v66, v66 row_ror:8 row_mask:0xf bank_mask:0xf bound_ctrl:1
	v_pk_fma_f32 v[26:27], v[26:27], v[88:89], v[64:65]
	v_fmac_f32_e32 v181, v28, v86
	v_add_f32_dpp v66, v66, v66 row_ror:4 row_mask:0xf bank_mask:0xf bound_ctrl:1
	v_fmac_f32_e32 v181, v29, v87
	v_pk_fma_f32 v[28:29], v[28:29], v[90:91], v[44:45]
	v_add_f32_dpp v66, v66, v66 row_ror:2 row_mask:0xf bank_mask:0xf bound_ctrl:1
	v_fmac_f32_e32 v135, v73, v81
	v_mov_b32_e32 v68, v193
	v_add_f32_dpp v66, v66, v66 row_ror:1 row_mask:0xf bank_mask:0xf bound_ctrl:1
	v_pk_fma_f32 v[26:27], v[66:67], v[104:105], v[26:27] op_sel_hi:[0,1,1]
	v_mul_f32_e32 v44, v100, v26
	v_pk_fma_f32 v[28:29], v[66:67], v[106:107], v[28:29] op_sel_hi:[0,1,1]
	v_fmac_f32_e32 v44, v27, v101
	v_fmac_f32_e32 v44, v28, v102
	v_fmac_f32_e32 v44, v29, v103
	v_pk_mul_f32 v[80:81], v[158:159], v[194:195] op_sel_hi:[1,0]
	v_mov_b32_e32 v112, v195
	v_add_f32_dpp v44, v44, v44 row_ror:8 row_mask:0xf bank_mask:0xf bound_ctrl:1
	v_pk_mul_f32 v[70:71], v[160:161], v[194:195] op_sel_hi:[1,0]
	v_mul_f32_e32 v195, v120, v26
	v_add_f32_dpp v44, v44, v44 row_ror:4 row_mask:0xf bank_mask:0xf bound_ctrl:1
	v_pk_mul_f32 v[72:73], v[116:117], v[68:69] op_sel_hi:[1,0]
	v_fmac_f32_e32 v195, v27, v121
	v_add_f32_dpp v44, v44, v44 row_ror:2 row_mask:0xf bank_mask:0xf bound_ctrl:1
	v_pk_mul_f32 v[68:69], v[118:119], v[68:69] op_sel_hi:[1,0]
	v_fmac_f32_e32 v195, v28, v122
	v_add_f32_dpp v44, v44, v44 row_ror:1 row_mask:0xf bank_mask:0xf bound_ctrl:1
	v_pk_fma_f32 v[26:27], v[26:27], v[92:93], v[72:73]
	v_fmac_f32_e32 v195, v29, v123
	v_pk_fma_f32 v[26:27], v[44:45], v[108:109], v[26:27] op_sel_hi:[0,1,1]
	v_pk_fma_f32 v[28:29], v[28:29], v[94:95], v[68:69]
	v_mul_f32_e32 v204, v124, v26
	v_pk_fma_f32 v[28:29], v[44:45], v[110:111], v[28:29] op_sel_hi:[0,1,1]
	v_mul_f32_e32 v44, v142, v26
	v_fmac_f32_e32 v44, v27, v143
	v_fmac_f32_e32 v44, v28, v144
	v_fmac_f32_e32 v44, v29, v145
	v_fmac_f32_e32 v204, v27, v125
	v_fmac_f32_e32 v204, v28, v126
	v_add_f32_dpp v44, v44, v44 row_ror:8 row_mask:0xf bank_mask:0xf bound_ctrl:1
	v_pk_fma_f32 v[26:27], v[26:27], v[128:129], v[80:81]
	v_fmac_f32_e32 v204, v29, v127
	v_add_f32_dpp v44, v44, v44 row_ror:4 row_mask:0xf bank_mask:0xf bound_ctrl:1
	v_pk_fma_f32 v[28:29], v[28:29], v[130:131], v[70:71]
; DI void scan_chunk(const float* buf, f32x4& S, int w, int rw, int kg, float& ys) {
;   float yp[16];
; #pragma unroll
;   for (int s = 0; s < 16; ++s) {
;     const float* b = buf + s * 64 + kg * 4;
;     f32x4 d = *(const f32x4*)(b), n = *(const f32x4*)(b + 1024), a = *(const f32x4*)(b + 2048), k = *(const f32x4*)(b + 3072),
;           r = *(const f32x4*)(b + 4096);
;     float vv = buf[5120 + s * 16 + w * 4 + rw];
;     float pp = S[0] * n[0];
;     pp = fmaf(S[1], n[1], pp); pp = fmaf(S[2], n[2], pp); pp = fmaf(S[3], n[3], pp);
;     float sa = row_allreduce(pp);
; #pragma unroll
;     for (int e = 0; e < 4; ++e) S[e] = fmaf(sa, a[e], fmaf(S[e], d[e], vv * k[e]));
;     float y = S[0] * r[0];
;     y = fmaf(S[1], r[1], y); y = fmaf(S[2], r[2], y); y = fmaf(S[3], r[3], y);
;     yp[s] = y;
;   }
	v_pk_mul_f32 v[116:117], v[162:163], v[112:113] op_sel_hi:[1,0]
	v_add_f32_dpp v44, v44, v44 row_ror:2 row_mask:0xf bank_mask:0xf bound_ctrl:1
	v_fmac_f32_e32 v135, v74, v82
	v_fmac_f32_e32 v135, v75, v83
	v_add_f32_dpp v44, v44, v44 row_ror:1 row_mask:0xf bank_mask:0xf bound_ctrl:1
	v_pk_fma_f32 v[26:27], v[44:45], v[150:151], v[26:27] op_sel_hi:[0,1,1]
	v_pk_fma_f32 v[28:29], v[44:45], v[152:153], v[28:29] op_sel_hi:[0,1,1]
	v_mul_f32_e32 v44, v146, v26
	v_fmac_f32_e32 v44, v27, v147
	v_fmac_f32_e32 v44, v28, v148
	v_fmac_f32_e32 v44, v29, v149
	v_mul_f32_e32 v206, v172, v26
	v_fmac_f32_e32 v206, v27, v173
	v_add_f32_dpp v44, v44, v44 row_ror:8 row_mask:0xf bank_mask:0xf bound_ctrl:1
	v_pk_fma_f32 v[26:27], v[26:27], v[138:139], v[116:117]
	v_fmac_f32_e32 v206, v28, v174
	v_add_f32_dpp v44, v44, v44 row_ror:4 row_mask:0xf bank_mask:0xf bound_ctrl:1
	v_fmac_f32_e32 v206, v29, v175
	s_cmp_ge_u32 s28, s39
	v_add_f32_dpp v44, v44, v44 row_ror:2 row_mask:0xf bank_mask:0xf bound_ctrl:1
	s_nop 1
	v_add_f32_dpp v44, v44, v44 row_ror:1 row_mask:0xf bank_mask:0xf bound_ctrl:1
	v_pk_fma_f32 v[190:191], v[44:45], v[154:155], v[26:27] op_sel_hi:[0,1,1]
	v_pk_mul_f32 v[26:27], v[164:165], v[112:113] op_sel_hi:[1,0]
	v_mul_f32_e32 v207, v182, v190
	v_pk_fma_f32 v[26:27], v[28:29], v[140:141], v[26:27]
	v_fmac_f32_e32 v207, v191, v183
	v_pk_fma_f32 v[44:45], v[44:45], v[156:157], v[26:27] op_sel_hi:[0,1,1]
	ds_read_b128 v[26:29], v51 offset:6656
	ds_read_b128 v[64:67], v51 offset:14848
	ds_read2_b32 v[192:193], v46 offset0:160 offset1:176
	ds_read_b128 v[68:71], v51 offset:6912
	v_fmac_f32_e32 v207, v44, v184
	v_fmac_f32_e32 v207, v45, v185
	s_waitcnt lgkmcnt(0)
	v_mul_f32_e32 v26, v26, v190
	v_fmac_f32_e32 v26, v191, v27
	v_fmac_f32_e32 v26, v44, v28
	v_fmac_f32_e32 v26, v45, v29
	v_pk_mul_f32 v[196:197], v[64:65], v[192:193] op_sel_hi:[1,0]
	v_pk_mul_f32 v[198:199], v[66:67], v[192:193] op_sel_hi:[1,0]
	v_add_f32_dpp v26, v26, v26 row_ror:8 row_mask:0xf bank_mask:0xf bound_ctrl:1
	s_nop 1
	v_add_f32_dpp v26, v26, v26 row_ror:4 row_mask:0xf bank_mask:0xf bound_ctrl:1
	s_nop 1
	v_add_f32_dpp v26, v26, v26 row_ror:2 row_mask:0xf bank_mask:0xf bound_ctrl:1
	s_nop 1
	v_add_f32_dpp v194, v26, v26 row_ror:1 row_mask:0xf bank_mask:0xf bound_ctrl:1
	ds_read_b128 v[26:29], v51 offset:15104
	ds_read_b128 v[64:67], v51 offset:2560
	ds_read_b128 v[72:75], v51 offset:2816
	ds_read_b128 v[76:79], v51 offset:10752
	ds_read_b128 v[80:83], v51 offset:11008
	ds_read_b128 v[84:87], v51 offset:18944
	ds_read_b128 v[88:91], v51 offset:19200
	ds_read2_b32 v[200:201], v46 offset0:192 offset1:208
	ds_read_b128 v[92:95], v51 offset:3072
	ds_read_b128 v[96:99], v51 offset:3328
	ds_read_b128 v[100:103], v51 offset:7168
	ds_read_b128 v[104:107], v51 offset:7424
	ds_read_b128 v[108:111], v51 offset:11264
	ds_read_b128 v[112:115], v51 offset:11520
	ds_read_b128 v[116:119], v51 offset:15360
	ds_read_b128 v[120:123], v51 offset:15616
	ds_read_b128 v[124:127], v51 offset:19456
	ds_read_b128 v[128:131], v51 offset:19712
	ds_read2_b32 v[202:203], v46 offset0:224 offset1:240
	ds_read_b128 v[138:141], v51 offset:3584
	ds_read_b128 v[142:145], v51 offset:3840
	ds_read_b128 v[146:149], v51 offset:7680
	ds_read_b128 v[150:153], v51 offset:7936
	ds_read_b128 v[154:157], v51 offset:11776
	ds_read_b128 v[158:161], v51 offset:12032
	ds_read_b128 v[162:165], v51 offset:15872
	ds_read_b128 v[172:175], v51 offset:16128
	ds_read_b128 v[182:185], v51 offset:19968
	ds_read_b128 v[186:189], v51 offset:20224
	s_waitcnt lgkmcnt(0)
	v_pk_fma_f32 v[64:65], v[190:191], v[64:65], v[196:197]
	v_pk_fma_f32 v[44:45], v[44:45], v[66:67], v[198:199]
	v_pk_fma_f32 v[64:65], v[194:195], v[76:77], v[64:65] op_sel_hi:[0,1,1]
	v_mul_f32_e32 v77, v68, v64
	v_pk_fma_f32 v[44:45], v[194:195], v[78:79], v[44:45] op_sel_hi:[0,1,1]
	v_fmac_f32_e32 v77, v65, v69
	v_mov_b32_e32 v46, v193
	v_mul_f32_e32 v76, v84, v64
	v_fmac_f32_e32 v77, v44, v70
	v_pk_mul_f32 v[28:29], v[28:29], v[46:47] op_sel_hi:[1,0]
	v_fmac_f32_e32 v76, v65, v85
	v_fmac_f32_e32 v77, v45, v71
	v_pk_fma_f32 v[28:29], v[44:45], v[74:75], v[28:29]
	v_fmac_f32_e32 v76, v44, v86
	v_add_f32_dpp v44, v77, v77 row_ror:8 row_mask:0xf bank_mask:0xf bound_ctrl:1
	v_pk_mul_f32 v[26:27], v[26:27], v[46:47] op_sel_hi:[1,0]
	v_fmac_f32_e32 v76, v45, v87
	v_add_f32_dpp v44, v44, v44 row_ror:4 row_mask:0xf bank_mask:0xf bound_ctrl:1
	v_pk_fma_f32 v[26:27], v[64:65], v[72:73], v[26:27]
	v_pk_mul_f32 v[64:65], v[116:117], v[200:201] op_sel_hi:[1,0]
	v_add_f32_dpp v44, v44, v44 row_ror:2 row_mask:0xf bank_mask:0xf bound_ctrl:1
	v_pk_mul_f32 v[66:67], v[118:119], v[200:201] op_sel_hi:[1,0]
	v_mov_b32_e32 v74, v201
	v_add_f32_dpp v44, v44, v44 row_ror:1 row_mask:0xf bank_mask:0xf bound_ctrl:1
	v_pk_fma_f32 v[26:27], v[44:45], v[80:81], v[26:27] op_sel_hi:[0,1,1]
	v_pk_fma_f32 v[28:29], v[44:45], v[82:83], v[28:29] op_sel_hi:[0,1,1]
	v_mul_f32_e32 v44, v100, v26
	v_fmac_f32_e32 v44, v27, v101
	v_fmac_f32_e32 v44, v28, v102
	v_fmac_f32_e32 v44, v29, v103
	v_mul_f32_e32 v45, v88, v26
	v_fmac_f32_e32 v45, v27, v89
	v_add_f32_dpp v44, v44, v44 row_ror:8 row_mask:0xf bank_mask:0xf bound_ctrl:1
	v_fmac_f32_e32 v45, v28, v90
	v_fmac_f32_e32 v45, v29, v91
	v_add_f32_dpp v44, v44, v44 row_ror:4 row_mask:0xf bank_mask:0xf bound_ctrl:1
	v_pk_fma_f32 v[26:27], v[26:27], v[92:93], v[64:65]
	v_pk_fma_f32 v[28:29], v[28:29], v[94:95], v[66:67]
	v_add_f32_dpp v44, v44, v44 row_ror:2 row_mask:0xf bank_mask:0xf bound_ctrl:1
	v_pk_mul_f32 v[68:69], v[120:121], v[74:75] op_sel_hi:[1,0]
	v_pk_mul_f32 v[78:79], v[122:123], v[74:75] op_sel_hi:[1,0]
	v_add_f32_dpp v44, v44, v44 row_ror:1 row_mask:0xf bank_mask:0xf bound_ctrl:1
; DI float bf2f(u16 h) { return __uint_as_float(((uint32_t)h) << 16); }
; DI f32x4 unpack4(u32x2 w) { return f32x4{bflo(w.x), bfhi(w.x), bflo(w.y), bfhi(w.y)}; }
; template <int CTRL> DI float dpp_get(float x) { return __int_as_float(__builtin_amdgcn_update_dpp(0, __float_as_int(x), CTRL, 0xf, 0xf, false)); }
; DI void scan_lstore(const int tid_, const ScanRegs& r, float* buf) {
;   const int tid = tid_;
;   {
;     int st = tid >> 4, c = tid & 15;
;     *(f32x4*)(buf + st * 64 + c * 4) = r.d;
;     buf[5120 + st * 16 + c] = bf2f(r.v);
;   }
;   {
;     int arr = tid >> 7, idx = tid & 127, st = idx >> 3, c8 = idx & 7;
;     float* d0 = buf + 1024 + arr * 1024 + st * 64 + c8 * 8;
;     float* d1 = buf + 3072 + arr * 1024 + st * 64 + c8 * 8;
;     *(f32x4*)(d0) = unpack4(u32x2{r.a0.x, r.a0.y});
;     *(f32x4*)(d0 + 4) = unpack4(u32x2{r.a0.z, r.a0.w});
;     *(f32x4*)(d1) = unpack4(u32x2{r.a1.x, r.a1.y});
;     *(f32x4*)(d1 + 4) = unpack4(u32x2{r.a1.z, r.a1.w});
;   }
; DI void scan_chunk(const float* buf, f32x4& S, int w, int rw, int kg, float& ys) {
;     ...
;   const bool b3 = (kg & 8) != 0, b2 = (kg & 4) != 0, b1 = (kg & 2) != 0, b0 = (kg & 1) != 0;
;   float t[8], u[4], v2[2];
; #pragma unroll
;   for (int j = 0; j < 8; ++j) { float keep = b3 ? yp[j + 8] : yp[j], send = b3 ? yp[j] : yp[j + 8]; t[j] = keep + dpp_get<0x140>(send); }
; #pragma unroll
;   for (int j = 0; j < 4; ++j) { float keep = b2 ? t[j + 4] : t[j], send = b2 ? t[j] : t[j + 4]; u[j] = keep + dpp_get<0x141>(send); }
; #pragma unroll
;   for (int j = 0; j < 2; ++j) { float keep = b1 ? u[j + 2] : u[j], send = b1 ? u[j] : u[j + 2]; v2[j] = keep + dpp_get<0x4E>(send); }
;   { float keep = b0 ? v2[1] : v2[0], send = b0 ? v2[0] : v2[1]; ys = keep + dpp_get<0xB1>(send); }
	v_pk_fma_f32 v[26:27], v[44:45], v[108:109], v[26:27] op_sel_hi:[0,1,1]
	v_pk_fma_f32 v[28:29], v[44:45], v[110:111], v[28:29] op_sel_hi:[0,1,1]
	v_mul_f32_e32 v44, v104, v26
	v_fmac_f32_e32 v44, v27, v105
	v_fmac_f32_e32 v44, v28, v106
	v_fmac_f32_e32 v44, v29, v107
	v_mul_f32_e32 v66, v124, v26
	v_fmac_f32_e32 v66, v27, v125
	v_add_f32_dpp v44, v44, v44 row_ror:8 row_mask:0xf bank_mask:0xf bound_ctrl:1
	v_fmac_f32_e32 v66, v28, v126
	v_pk_fma_f32 v[26:27], v[26:27], v[96:97], v[68:69]
	v_add_f32_dpp v44, v44, v44 row_ror:4 row_mask:0xf bank_mask:0xf bound_ctrl:1
	v_fmac_f32_e32 v66, v29, v127
	v_pk_fma_f32 v[28:29], v[28:29], v[98:99], v[78:79]
	v_add_f32_dpp v44, v44, v44 row_ror:2 row_mask:0xf bank_mask:0xf bound_ctrl:1
	v_pk_mul_f32 v[72:73], v[162:163], v[202:203] op_sel_hi:[1,0]
	v_pk_mul_f32 v[118:119], v[164:165], v[202:203] op_sel_hi:[1,0]
	v_add_f32_dpp v44, v44, v44 row_ror:1 row_mask:0xf bank_mask:0xf bound_ctrl:1
	v_pk_fma_f32 v[26:27], v[44:45], v[112:113], v[26:27] op_sel_hi:[0,1,1]
	v_pk_fma_f32 v[28:29], v[44:45], v[114:115], v[28:29] op_sel_hi:[0,1,1]
	v_mul_f32_e32 v44, v146, v26
	v_fmac_f32_e32 v44, v27, v147
	v_fmac_f32_e32 v44, v28, v148
	v_fmac_f32_e32 v44, v29, v149
	v_mul_f32_e32 v67, v128, v26
	v_fmac_f32_e32 v67, v27, v129
	v_add_f32_dpp v44, v44, v44 row_ror:8 row_mask:0xf bank_mask:0xf bound_ctrl:1
	v_fmac_f32_e32 v67, v28, v130
	v_pk_fma_f32 v[26:27], v[26:27], v[138:139], v[72:73]
	v_add_f32_dpp v44, v44, v44 row_ror:4 row_mask:0xf bank_mask:0xf bound_ctrl:1
	v_fmac_f32_e32 v67, v29, v131
	v_pk_fma_f32 v[28:29], v[28:29], v[140:141], v[118:119]
	v_add_f32_dpp v44, v44, v44 row_ror:2 row_mask:0xf bank_mask:0xf bound_ctrl:1
	v_mov_b32_e32 v46, v203
	v_pk_mul_f32 v[74:75], v[172:173], v[46:47] op_sel_hi:[1,0]
	v_add_f32_dpp v44, v44, v44 row_ror:1 row_mask:0xf bank_mask:0xf bound_ctrl:1
	v_pk_fma_f32 v[26:27], v[44:45], v[154:155], v[26:27] op_sel_hi:[0,1,1]
	v_pk_fma_f32 v[28:29], v[44:45], v[156:157], v[28:29] op_sel_hi:[0,1,1]
	v_mul_f32_e32 v44, v150, v26
	v_fmac_f32_e32 v44, v27, v151
	v_fmac_f32_e32 v44, v28, v152
	v_fmac_f32_e32 v44, v29, v153
	v_mul_f32_e32 v68, v182, v26
	v_fmac_f32_e32 v68, v27, v183
	v_add_f32_dpp v44, v44, v44 row_ror:8 row_mask:0xf bank_mask:0xf bound_ctrl:1
	v_pk_mul_f32 v[64:65], v[174:175], v[46:47] op_sel_hi:[1,0]
	v_cndmask_b32_e64 v46, v206, v0, s[40:41]
	v_add_f32_dpp v44, v44, v44 row_ror:4 row_mask:0xf bank_mask:0xf bound_ctrl:1
	v_cndmask_b32_e64 v0, v0, v206, s[40:41]
	v_fmac_f32_e32 v68, v28, v184
	v_add_f32_dpp v44, v44, v44 row_ror:2 row_mask:0xf bank_mask:0xf bound_ctrl:1
	v_pk_fma_f32 v[26:27], v[26:27], v[142:143], v[74:75]
	v_add_f32_dpp v0, v0, v46 row_mirror row_mask:0xf bank_mask:0xf bound_ctrl:1
	v_add_f32_dpp v44, v44, v44 row_ror:1 row_mask:0xf bank_mask:0xf bound_ctrl:1
	v_cndmask_b32_e64 v46, v207, v47, s[40:41]
	v_cndmask_b32_e64 v47, v47, v207, s[40:41]
	v_fmac_f32_e32 v68, v29, v185
	v_pk_fma_f32 v[26:27], v[44:45], v[158:159], v[26:27] op_sel_hi:[0,1,1]
	v_pk_fma_f32 v[28:29], v[28:29], v[144:145], v[64:65]
	v_add_f32_dpp v46, v47, v46 row_mirror row_mask:0xf bank_mask:0xf bound_ctrl:1
	v_cndmask_b32_e64 v47, v76, v62, s[40:41]
	v_cndmask_b32_e64 v62, v62, v76, s[40:41]
	v_pk_fma_f32 v[28:29], v[44:45], v[160:161], v[28:29] op_sel_hi:[0,1,1]
	v_mul_f32_e32 v44, v186, v26
	v_add_f32_dpp v47, v62, v47 row_mirror row_mask:0xf bank_mask:0xf bound_ctrl:1
	v_cndmask_b32_e64 v62, v45, v63, s[40:41]
	v_cndmask_b32_e64 v45, v63, v45, s[40:41]
	v_fmac_f32_e32 v44, v27, v187
	v_cndmask_b32_e64 v63, v135, v66, s[40:41]
	v_add_f32_dpp v45, v45, v62 row_mirror row_mask:0xf bank_mask:0xf bound_ctrl:1
	v_cndmask_b32_e64 v62, v66, v135, s[40:41]
	v_fmac_f32_e32 v44, v28, v188
	v_cndmask_b32_e64 v64, v181, v67, s[40:41]
	v_add_f32_dpp v62, v63, v62 row_mirror row_mask:0xf bank_mask:0xf bound_ctrl:1
	v_cndmask_b32_e64 v63, v67, v181, s[40:41]
	v_fmac_f32_e32 v44, v29, v189
	v_cndmask_b32_e64 v65, v195, v68, s[40:41]
	v_add_f32_dpp v63, v64, v63 row_mirror row_mask:0xf bank_mask:0xf bound_ctrl:1
	v_cndmask_b32_e64 v64, v68, v195, s[40:41]
	s_nop 1
	v_add_f32_dpp v64, v65, v64 row_mirror row_mask:0xf bank_mask:0xf bound_ctrl:1
	v_cndmask_b32_e64 v65, v44, v204, s[40:41]
	v_cndmask_b32_e64 v44, v204, v44, s[40:41]
	s_nop 1
	v_add_f32_dpp v44, v44, v65 row_mirror row_mask:0xf bank_mask:0xf bound_ctrl:1
	v_cndmask_b32_e64 v65, v62, v0, s[42:43]
	v_cndmask_b32_e64 v0, v0, v62, s[42:43]
	v_cndmask_b32_e64 v62, v63, v46, s[42:43]
	v_cndmask_b32_e64 v46, v46, v63, s[42:43]
	v_add_f32_dpp v0, v0, v65 row_half_mirror row_mask:0xf bank_mask:0xf bound_ctrl:1
	s_nop 0
	v_add_f32_dpp v46, v46, v62 row_half_mirror row_mask:0xf bank_mask:0xf bound_ctrl:1
	v_cndmask_b32_e64 v62, v64, v47, s[42:43]
	v_cndmask_b32_e64 v47, v47, v64, s[42:43]
	s_nop 1
	v_add_f32_dpp v47, v47, v62 row_half_mirror row_mask:0xf bank_mask:0xf bound_ctrl:1
	v_cndmask_b32_e64 v62, v44, v45, s[42:43]
	v_cndmask_b32_e64 v44, v45, v44, s[42:43]
	v_cndmask_b32_e64 v45, v47, v0, s[44:45]
	v_cndmask_b32_e64 v0, v0, v47, s[44:45]
	v_add_f32_dpp v44, v44, v62 row_half_mirror row_mask:0xf bank_mask:0xf bound_ctrl:1
	s_nop 0
	v_add_f32_dpp v0, v0, v45 quad_perm:[2,3,0,1] row_mask:0xf bank_mask:0xf bound_ctrl:1
	v_cndmask_b32_e64 v45, v44, v46, s[44:45]
	v_cndmask_b32_e64 v44, v46, v44, s[44:45]
	s_nop 1
	v_add_f32_dpp v44, v44, v45 quad_perm:[2,3,0,1] row_mask:0xf bank_mask:0xf bound_ctrl:1
	v_cndmask_b32_e64 v45, v44, v0, s[46:47]
	v_cndmask_b32_e64 v0, v0, v44, s[46:47]
	v_add_u32_e32 v44, s38, v43
	s_nop 0
	v_add_f32_dpp v0, v0, v45 quad_perm:[1,0,3,2] row_mask:0xf bank_mask:0xf bound_ctrl:1
	v_ashrrev_i32_e32 v45, 31, v44
	v_lshlrev_b64 v[46:47], 11, v[44:45]
	v_lshl_add_u64 v[46:47], v[36:37], 0, v[46:47]
	flat_store_dword v[46:47], v0
	s_cbranch_scc1 .LBB0_188
	s_waitcnt vmcnt(1)
	v_lshlrev_b32_e32 v0, 16, v50
	v_lshlrev_b32_e32 v62, 16, v6
	v_and_b32_e32 v63, 0xffff0000, v6
	v_lshlrev_b32_e32 v64, 16, v7
	v_and_b32_e32 v65, 0xffff0000, v7
	ds_write_b128 v57, v[2:5]
	ds_write_b32 v58, v0 offset:20480
	ds_write_b128 v59, v[62:65] offset:4096
	v_lshlrev_b32_e32 v62, 16, v8
	v_and_b32_e32 v63, 0xffff0000, v8
	v_lshlrev_b32_e32 v64, 16, v9
	v_and_b32_e32 v65, 0xffff0000, v9
	ds_write_b128 v59, v[62:65] offset:4112
	v_lshlrev_b32_e32 v62, 16, v10
	v_and_b32_e32 v63, 0xffff0000, v10
	v_lshlrev_b32_e32 v64, 16, v11
	v_and_b32_e32 v65, 0xffff0000, v11
	ds_write_b128 v59, v[62:65] offset:12288
	v_lshlrev_b32_e32 v62, 16, v12
	v_and_b32_e32 v63, 0xffff0000, v12
	v_lshlrev_b32_e32 v64, 16, v13
	v_and_b32_e32 v65, 0xffff0000, v13
	ds_write_b128 v59, v[62:65] offset:12304
; DI void scan_chunk(const float* buf, f32x4& S, int w, int rw, int kg, float& ys) {
;   float yp[16];
; #pragma unroll
;   for (int s = 0; s < 16; ++s) {
;     const float* b = buf + s * 64 + kg * 4;
;     f32x4 d = *(const f32x4*)(b), n = *(const f32x4*)(b + 1024), a = *(const f32x4*)(b + 2048), k = *(const f32x4*)(b + 3072),
;           r = *(const f32x4*)(b + 4096);
;     float vv = buf[5120 + s * 16 + w * 4 + rw];
;     float pp = S[0] * n[0];
;     pp = fmaf(S[1], n[1], pp); pp = fmaf(S[2], n[2], pp); pp = fmaf(S[3], n[3], pp);
;     float sa = row_allreduce(pp);
; #pragma unroll
;     for (int e = 0; e < 4; ++e) S[e] = fmaf(sa, a[e], fmaf(S[e], d[e], vv * k[e]));
;     float y = S[0] * r[0];
;     y = fmaf(S[1], r[1], y); y = fmaf(S[2], r[2], y); y = fmaf(S[3], r[3], y);
;     yp[s] = y;
;   }
; DI void scan_job(const int tid_, const Params& p, int l, int job, char* s0, char* s1, char* s2) {
;     ...
;     __syncthreads();
;     if (c + 1 < nchunks) {
;       if (c + 3 < nchunks) scan_gload(tid_, A, p, tok0 + (c + 3) * 16, h, rg);
;       ys = 0.f;
;       scan_chunk(buf1, S, w, rw, kg, ys);
.LBB0_188:
	s_andn2_b64 vcc, exec, s[8:9]
	s_waitcnt lgkmcnt(0)
	s_barrier
	s_cbranch_vccnz .LBB0_183
	s_cmp_ge_u32 s20, s39
	s_cbranch_scc1 .LBB0_191
	s_waitcnt vmcnt(1)
	v_add3_u32 v2, v48, s38, 48
	v_ashrrev_i32_e32 v3, 31, v2
	v_lshlrev_b64 v[4:5], 11, v[2:3]
	v_lshlrev_b64 v[2:3], 10, v[2:3]
	v_lshl_add_u64 v[4:5], v[38:39], 0, v[4:5]
	v_lshl_add_u64 v[6:7], v[40:41], 0, v[2:3]
	v_add3_u32 v0, v49, s38, 48
	flat_load_dwordx4 v[2:5], v[4:5]
	s_nop 0
	flat_load_ushort v50, v[6:7]
	v_lshlrev_b64 v[6:7], 10, v[0:1]
	v_lshl_or_b32 v6, v42, 1, v6
	v_lshl_add_u64 v[8:9], v[32:33], 0, v[6:7]
	v_lshl_add_u64 v[10:11], v[34:35], 0, v[6:7]
	flat_load_dwordx4 v[6:9], v[8:9]
	s_nop 0
	flat_load_dwordx4 v[10:13], v[10:11]
.LBB0_191:
	ds_read_b128 v[62:65], v56 offset:4096
	v_add_u32_e32 v45, 0x5000, v60
	ds_read_b128 v[66:69], v56 offset:4352
	ds_read2_b32 v[46:47], v45 offset1:16
	s_andn2_b64 vcc, exec, s[30:31]
	s_waitcnt lgkmcnt(0)
	v_mul_f32_e32 v0, v26, v62
	v_fmac_f32_e32 v0, v27, v63
	v_fmac_f32_e32 v0, v28, v64
	v_fmac_f32_e32 v0, v29, v65
	ds_read_b128 v[62:65], v56
	ds_read_b128 v[70:73], v56 offset:256
	ds_read_b128 v[74:77], v56 offset:8192
	ds_read_b128 v[78:81], v56 offset:8448
	ds_read_b128 v[82:85], v56 offset:12288
	ds_read_b128 v[86:89], v56 offset:12544
	ds_read_b128 v[90:93], v56 offset:16384
	ds_read_b128 v[94:97], v56 offset:16640
	ds_read2_b32 v[182:183], v45 offset0:32 offset1:48
	ds_read_b128 v[98:101], v56 offset:512
	ds_read_b128 v[102:105], v56 offset:768
	ds_read_b128 v[106:109], v56 offset:4608
	ds_read_b128 v[110:113], v56 offset:4864
	ds_read_b128 v[114:117], v56 offset:8704
	ds_read_b128 v[118:121], v56 offset:8960
	ds_read_b128 v[122:125], v56 offset:12800
	ds_read_b128 v[126:129], v56 offset:13056
	ds_read_b128 v[138:141], v56 offset:16896
	ds_read_b128 v[142:145], v56 offset:17152
	ds_read_b128 v[146:149], v56 offset:1024
	ds_read_b128 v[150:153], v56 offset:5120
	ds_read_b128 v[154:157], v56 offset:9216
	ds_read_b128 v[158:161], v56 offset:13312
	ds_read_b128 v[162:165], v56 offset:17408
	ds_read2_b32 v[184:185], v45 offset0:64 offset1:80
	v_add_f32_dpp v0, v0, v0 row_ror:8 row_mask:0xf bank_mask:0xf bound_ctrl:1
	s_waitcnt lgkmcnt(0)
	v_pk_mul_f32 v[82:83], v[82:83], v[46:47] op_sel_hi:[1,0]
	ds_read_b128 v[172:175], v56 offset:13568
	v_add_f32_dpp v0, v0, v0 row_ror:4 row_mask:0xf bank_mask:0xf bound_ctrl:1
	v_pk_fma_f32 v[26:27], v[26:27], v[62:63], v[82:83]
	v_mov_b32_e32 v62, v47
	v_add_f32_dpp v0, v0, v0 row_ror:2 row_mask:0xf bank_mask:0xf bound_ctrl:1
	v_pk_mul_f32 v[46:47], v[84:85], v[46:47] op_sel_hi:[1,0]
	v_pk_mul_f32 v[82:83], v[158:159], v[184:185] op_sel_hi:[1,0]
	v_add_f32_dpp v130, v0, v0 row_ror:1 row_mask:0xf bank_mask:0xf bound_ctrl:1
	v_pk_fma_f32 v[26:27], v[130:131], v[74:75], v[26:27] op_sel_hi:[0,1,1]
	v_mul_f32_e32 v63, v66, v26
	v_pk_fma_f32 v[28:29], v[28:29], v[64:65], v[46:47]
	v_fmac_f32_e32 v63, v27, v67
	v_pk_fma_f32 v[28:29], v[130:131], v[76:77], v[28:29] op_sel_hi:[0,1,1]
	v_mul_f32_e32 v0, v90, v26
	v_pk_mul_f32 v[66:67], v[86:87], v[62:63] op_sel_hi:[1,0]
	v_pk_mul_f32 v[46:47], v[88:89], v[62:63] op_sel_hi:[1,0]
	v_fmac_f32_e32 v63, v28, v68
	v_fmac_f32_e32 v0, v27, v91
	v_fmac_f32_e32 v63, v29, v69
	v_pk_fma_f32 v[46:47], v[28:29], v[72:73], v[46:47]
	v_fmac_f32_e32 v0, v28, v92
	v_add_f32_dpp v28, v63, v63 row_ror:8 row_mask:0xf bank_mask:0xf bound_ctrl:1
	v_pk_fma_f32 v[26:27], v[26:27], v[70:71], v[66:67]
	v_fmac_f32_e32 v0, v29, v93
	v_add_f32_dpp v28, v28, v28 row_ror:4 row_mask:0xf bank_mask:0xf bound_ctrl:1
	v_pk_mul_f32 v[66:67], v[122:123], v[182:183] op_sel_hi:[1,0]
	v_pk_mul_f32 v[64:65], v[124:125], v[182:183] op_sel_hi:[1,0]
	v_add_f32_dpp v28, v28, v28 row_ror:2 row_mask:0xf bank_mask:0xf bound_ctrl:1
	v_mov_b32_e32 v70, v183
	v_pk_mul_f32 v[74:75], v[126:127], v[70:71] op_sel_hi:[1,0]
	v_add_f32_dpp v28, v28, v28 row_ror:1 row_mask:0xf bank_mask:0xf bound_ctrl:1
	v_pk_fma_f32 v[26:27], v[28:29], v[78:79], v[26:27] op_sel_hi:[0,1,1]
	v_pk_fma_f32 v[28:29], v[28:29], v[80:81], v[46:47] op_sel_hi:[0,1,1]
	v_mul_f32_e32 v46, v106, v26
	v_fmac_f32_e32 v46, v27, v107
	v_fmac_f32_e32 v46, v28, v108
	v_fmac_f32_e32 v46, v29, v109
	v_mul_f32_e32 v62, v94, v26
	v_fmac_f32_e32 v62, v27, v95
	v_add_f32_dpp v46, v46, v46 row_ror:8 row_mask:0xf bank_mask:0xf bound_ctrl:1
	v_fmac_f32_e32 v62, v28, v96
	v_pk_fma_f32 v[26:27], v[26:27], v[98:99], v[66:67]
	v_add_f32_dpp v46, v46, v46 row_ror:4 row_mask:0xf bank_mask:0xf bound_ctrl:1
	v_fmac_f32_e32 v62, v29, v97
	v_pk_fma_f32 v[28:29], v[28:29], v[100:101], v[64:65]
	v_add_f32_dpp v46, v46, v46 row_ror:2 row_mask:0xf bank_mask:0xf bound_ctrl:1
	v_pk_mul_f32 v[70:71], v[128:129], v[70:71] op_sel_hi:[1,0]
	ds_read_b128 v[66:69], v56 offset:1280
	v_add_f32_dpp v46, v46, v46 row_ror:1 row_mask:0xf bank_mask:0xf bound_ctrl:1
	v_pk_fma_f32 v[26:27], v[46:47], v[114:115], v[26:27] op_sel_hi:[0,1,1]
	v_pk_fma_f32 v[28:29], v[46:47], v[116:117], v[28:29] op_sel_hi:[0,1,1]
	v_mul_f32_e32 v46, v110, v26
	v_fmac_f32_e32 v46, v27, v111
	v_fmac_f32_e32 v46, v28, v112
	v_fmac_f32_e32 v46, v29, v113
	v_mul_f32_e32 v63, v138, v26
	v_fmac_f32_e32 v63, v27, v139
	v_add_f32_dpp v46, v46, v46 row_ror:8 row_mask:0xf bank_mask:0xf bound_ctrl:1
	v_pk_fma_f32 v[26:27], v[26:27], v[102:103], v[74:75]
	v_fmac_f32_e32 v63, v28, v140
	v_add_f32_dpp v46, v46, v46 row_ror:4 row_mask:0xf bank_mask:0xf bound_ctrl:1
	v_fmac_f32_e32 v63, v29, v141
	s_nop 0
	v_add_f32_dpp v46, v46, v46 row_ror:2 row_mask:0xf bank_mask:0xf bound_ctrl:1
	s_nop 1
	v_add_f32_dpp v46, v46, v46 row_ror:1 row_mask:0xf bank_mask:0xf bound_ctrl:1
	v_pk_fma_f32 v[72:73], v[46:47], v[118:119], v[26:27] op_sel_hi:[0,1,1]
	v_pk_fma_f32 v[26:27], v[28:29], v[104:105], v[70:71]
	v_mul_f32_e32 v65, v150, v72
	v_pk_fma_f32 v[46:47], v[46:47], v[120:121], v[26:27] op_sel_hi:[0,1,1]
	v_fmac_f32_e32 v65, v73, v151
	v_fmac_f32_e32 v65, v46, v152
	v_fmac_f32_e32 v65, v47, v153
	ds_read_b128 v[26:29], v56 offset:5376
	v_mul_f32_e32 v64, v142, v72
	v_add_f32_dpp v65, v65, v65 row_ror:8 row_mask:0xf bank_mask:0xf bound_ctrl:1
	v_fmac_f32_e32 v64, v73, v143
	v_pk_fma_f32 v[76:77], v[72:73], v[146:147], v[82:83]
	v_add_f32_dpp v65, v65, v65 row_ror:4 row_mask:0xf bank_mask:0xf bound_ctrl:1
	v_fmac_f32_e32 v64, v46, v144
	v_fmac_f32_e32 v64, v47, v145
	v_add_f32_dpp v65, v65, v65 row_ror:2 row_mask:0xf bank_mask:0xf bound_ctrl:1
	ds_read_b128 v[70:73], v56 offset:9472
	s_nop 0
	v_add_f32_dpp v74, v65, v65 row_ror:1 row_mask:0xf bank_mask:0xf bound_ctrl:1
	v_pk_fma_f32 v[130:131], v[74:75], v[154:155], v[76:77] op_sel_hi:[0,1,1]
	v_pk_mul_f32 v[76:77], v[160:161], v[184:185] op_sel_hi:[1,0]
	s_waitcnt lgkmcnt(0)
; DI void scan_chunk(const float* buf, f32x4& S, int w, int rw, int kg, float& ys) {
;   float yp[16];
; #pragma unroll
;   for (int s = 0; s < 16; ++s) {
;     const float* b = buf + s * 64 + kg * 4;
;     f32x4 d = *(const f32x4*)(b), n = *(const f32x4*)(b + 1024), a = *(const f32x4*)(b + 2048), k = *(const f32x4*)(b + 3072),
;           r = *(const f32x4*)(b + 4096);
;     float vv = buf[5120 + s * 16 + w * 4 + rw];
;     float pp = S[0] * n[0];
;     pp = fmaf(S[1], n[1], pp); pp = fmaf(S[2], n[2], pp); pp = fmaf(S[3], n[3], pp);
;     float sa = row_allreduce(pp);
; #pragma unroll
;     for (int e = 0; e < 4; ++e) S[e] = fmaf(sa, a[e], fmaf(S[e], d[e], vv * k[e]));
;     float y = S[0] * r[0];
;     y = fmaf(S[1], r[1], y); y = fmaf(S[2], r[2], y); y = fmaf(S[3], r[3], y);
;     yp[s] = y;
;   }
	v_mul_f32_e32 v26, v26, v130
	v_pk_fma_f32 v[46:47], v[46:47], v[148:149], v[76:77]
	v_fmac_f32_e32 v26, v131, v27
	v_pk_fma_f32 v[186:187], v[74:75], v[156:157], v[46:47] op_sel_hi:[0,1,1]
	v_fmac_f32_e32 v26, v186, v28
	v_fmac_f32_e32 v26, v187, v29
	ds_read_b128 v[74:77], v56 offset:17664
	v_mul_f32_e32 v65, v162, v130
	v_add_f32_dpp v26, v26, v26 row_ror:8 row_mask:0xf bank_mask:0xf bound_ctrl:1
	v_fmac_f32_e32 v65, v131, v163
	v_fmac_f32_e32 v65, v186, v164
	v_add_f32_dpp v26, v26, v26 row_ror:4 row_mask:0xf bank_mask:0xf bound_ctrl:1
	v_fmac_f32_e32 v65, v187, v165
	s_nop 0
	v_add_f32_dpp v26, v26, v26 row_ror:2 row_mask:0xf bank_mask:0xf bound_ctrl:1
	s_nop 1
	v_add_f32_dpp v188, v26, v26 row_ror:1 row_mask:0xf bank_mask:0xf bound_ctrl:1
	v_mov_b32_e32 v26, v185
	v_pk_mul_f32 v[190:191], v[172:173], v[26:27] op_sel_hi:[1,0]
	v_pk_mul_f32 v[192:193], v[174:175], v[26:27] op_sel_hi:[1,0]
	v_pk_fma_f32 v[66:67], v[130:131], v[66:67], v[190:191]
	ds_read2_b32 v[194:195], v45 offset0:96 offset1:112
	ds_read_b128 v[78:81], v56 offset:1536
	ds_read_b128 v[82:85], v56 offset:1792
	ds_read_b128 v[86:89], v56 offset:5632
	ds_read_b128 v[90:93], v56 offset:5888
	ds_read_b128 v[94:97], v56 offset:9728
	ds_read_b128 v[98:101], v56 offset:9984
	ds_read_b128 v[102:105], v56 offset:13824
	ds_read_b128 v[106:109], v56 offset:14080
	ds_read_b128 v[110:113], v56 offset:17920
	ds_read_b128 v[114:117], v56 offset:18176
	ds_read2_b32 v[196:197], v45 offset0:128 offset1:144
	ds_read_b128 v[118:121], v56 offset:2048
	ds_read_b128 v[122:125], v56 offset:2304
	ds_read_b128 v[126:129], v56 offset:6144
	ds_read_b128 v[138:141], v56 offset:6400
	ds_read_b128 v[142:145], v56 offset:10240
	ds_read_b128 v[146:149], v56 offset:10496
	ds_read_b128 v[150:153], v56 offset:14336
	ds_read_b128 v[154:157], v56 offset:14592
	ds_read_b128 v[158:161], v56 offset:18432
	ds_read_b128 v[162:165], v56 offset:18688
	ds_read_b128 v[26:29], v56 offset:2560
	ds_read_b128 v[172:175], v56 offset:6656
	ds_read_b128 v[182:185], v56 offset:14848
	ds_read2_b32 v[46:47], v45 offset0:160 offset1:176
	v_pk_fma_f32 v[66:67], v[188:189], v[70:71], v[66:67] op_sel_hi:[0,1,1]
	v_pk_fma_f32 v[68:69], v[186:187], v[68:69], v[192:193]
	s_waitcnt lgkmcnt(0)
	v_mul_f32_e32 v130, v86, v66
	v_pk_fma_f32 v[72:73], v[188:189], v[72:73], v[68:69] op_sel_hi:[0,1,1]
	v_fmac_f32_e32 v130, v67, v87
	v_mul_f32_e32 v131, v74, v66
	v_fmac_f32_e32 v130, v72, v88
	v_pk_mul_f32 v[68:69], v[104:105], v[194:195] op_sel_hi:[1,0]
	v_fmac_f32_e32 v131, v67, v75
	v_fmac_f32_e32 v130, v73, v89
	v_pk_fma_f32 v[80:81], v[72:73], v[80:81], v[68:69]
	v_fmac_f32_e32 v131, v72, v76
	v_add_f32_dpp v72, v130, v130 row_ror:8 row_mask:0xf bank_mask:0xf bound_ctrl:1
	v_pk_mul_f32 v[70:71], v[102:103], v[194:195] op_sel_hi:[1,0]
	v_fmac_f32_e32 v131, v73, v77
	v_add_f32_dpp v72, v72, v72 row_ror:4 row_mask:0xf bank_mask:0xf bound_ctrl:1
	v_pk_fma_f32 v[70:71], v[66:67], v[78:79], v[70:71]
	v_mov_b32_e32 v68, v195
	v_add_f32_dpp v72, v72, v72 row_ror:2 row_mask:0xf bank_mask:0xf bound_ctrl:1
	v_pk_mul_f32 v[74:75], v[106:107], v[68:69] op_sel_hi:[1,0]
	v_pk_mul_f32 v[104:105], v[108:109], v[68:69] op_sel_hi:[1,0]
	v_add_f32_dpp v72, v72, v72 row_ror:1 row_mask:0xf bank_mask:0xf bound_ctrl:1
	v_pk_fma_f32 v[70:71], v[72:73], v[94:95], v[70:71] op_sel_hi:[0,1,1]
	v_mul_f32_e32 v76, v90, v70
	v_pk_fma_f32 v[72:73], v[72:73], v[96:97], v[80:81] op_sel_hi:[0,1,1]
	v_fmac_f32_e32 v76, v71, v91
	v_fmac_f32_e32 v76, v72, v92
	v_fmac_f32_e32 v76, v73, v93
	v_mul_f32_e32 v135, v110, v70
	v_fmac_f32_e32 v135, v71, v111
	v_add_f32_dpp v76, v76, v76 row_ror:8 row_mask:0xf bank_mask:0xf bound_ctrl:1
	v_pk_fma_f32 v[70:71], v[70:71], v[82:83], v[74:75]
	v_fmac_f32_e32 v135, v72, v112
	v_add_f32_dpp v76, v76, v76 row_ror:4 row_mask:0xf bank_mask:0xf bound_ctrl:1
	v_fmac_f32_e32 v135, v73, v113
	v_pk_fma_f32 v[72:73], v[72:73], v[84:85], v[104:105]
	v_add_f32_dpp v76, v76, v76 row_ror:2 row_mask:0xf bank_mask:0xf bound_ctrl:1
	v_pk_mul_f32 v[78:79], v[150:151], v[196:197] op_sel_hi:[1,0]
	v_pk_mul_f32 v[108:109], v[152:153], v[196:197] op_sel_hi:[1,0]
	v_add_f32_dpp v76, v76, v76 row_ror:1 row_mask:0xf bank_mask:0xf bound_ctrl:1
	v_pk_fma_f32 v[70:71], v[76:77], v[98:99], v[70:71] op_sel_hi:[0,1,1]
	v_mul_f32_e32 v74, v126, v70
	v_pk_fma_f32 v[72:73], v[76:77], v[100:101], v[72:73] op_sel_hi:[0,1,1]
	v_fmac_f32_e32 v74, v71, v127
	v_fmac_f32_e32 v74, v72, v128
	v_fmac_f32_e32 v74, v73, v129
	v_mul_f32_e32 v181, v114, v70
	v_fmac_f32_e32 v181, v71, v115
	v_add_f32_dpp v74, v74, v74 row_ror:8 row_mask:0xf bank_mask:0xf bound_ctrl:1
	v_fmac_f32_e32 v181, v72, v116
	v_pk_fma_f32 v[70:71], v[70:71], v[118:119], v[78:79]
	v_add_f32_dpp v74, v74, v74 row_ror:4 row_mask:0xf bank_mask:0xf bound_ctrl:1
	v_fmac_f32_e32 v181, v73, v117
	v_pk_fma_f32 v[72:73], v[72:73], v[120:121], v[108:109]
	v_add_f32_dpp v74, v74, v74 row_ror:2 row_mask:0xf bank_mask:0xf bound_ctrl:1
	v_mov_b32_e32 v152, v197
	v_pk_mul_f32 v[86:87], v[154:155], v[152:153] op_sel_hi:[1,0]
	v_add_f32_dpp v74, v74, v74 row_ror:1 row_mask:0xf bank_mask:0xf bound_ctrl:1
	v_pk_fma_f32 v[70:71], v[74:75], v[142:143], v[70:71] op_sel_hi:[0,1,1]
	v_pk_fma_f32 v[72:73], v[74:75], v[144:145], v[72:73] op_sel_hi:[0,1,1]
	v_mul_f32_e32 v74, v138, v70
	v_fmac_f32_e32 v74, v71, v139
	v_fmac_f32_e32 v74, v72, v140
	v_fmac_f32_e32 v74, v73, v141
	v_mul_f32_e32 v198, v158, v70
	v_pk_mul_f32 v[156:157], v[156:157], v[152:153] op_sel_hi:[1,0]
	v_add_f32_dpp v74, v74, v74 row_ror:8 row_mask:0xf bank_mask:0xf bound_ctrl:1
	v_fmac_f32_e32 v198, v71, v159
	v_pk_fma_f32 v[70:71], v[70:71], v[122:123], v[86:87]
; DI void scan_chunk(const float* buf, f32x4& S, int w, int rw, int kg, float& ys) {
;   float yp[16];
; #pragma unroll
;   for (int s = 0; s < 16; ++s) {
;     const float* b = buf + s * 64 + kg * 4;
;     f32x4 d = *(const f32x4*)(b), n = *(const f32x4*)(b + 1024), a = *(const f32x4*)(b + 2048), k = *(const f32x4*)(b + 3072),
;           r = *(const f32x4*)(b + 4096);
;     float vv = buf[5120 + s * 16 + w * 4 + rw];
;     float pp = S[0] * n[0];
;     pp = fmaf(S[1], n[1], pp); pp = fmaf(S[2], n[2], pp); pp = fmaf(S[3], n[3], pp);
;     float sa = row_allreduce(pp);
; #pragma unroll
;     for (int e = 0; e < 4; ++e) S[e] = fmaf(sa, a[e], fmaf(S[e], d[e], vv * k[e]));
;     float y = S[0] * r[0];
;     y = fmaf(S[1], r[1], y); y = fmaf(S[2], r[2], y); y = fmaf(S[3], r[3], y);
;     yp[s] = y;
;   }
	v_add_f32_dpp v74, v74, v74 row_ror:4 row_mask:0xf bank_mask:0xf bound_ctrl:1
	v_fmac_f32_e32 v198, v72, v160
	v_fmac_f32_e32 v198, v73, v161
	v_add_f32_dpp v74, v74, v74 row_ror:2 row_mask:0xf bank_mask:0xf bound_ctrl:1
	v_pk_mul_f32 v[102:103], v[182:183], v[46:47] op_sel_hi:[1,0]
	ds_read_b128 v[66:69], v56 offset:15104
	v_add_f32_dpp v74, v74, v74 row_ror:1 row_mask:0xf bank_mask:0xf bound_ctrl:1
	v_pk_fma_f32 v[78:79], v[74:75], v[146:147], v[70:71] op_sel_hi:[0,1,1]
	v_pk_fma_f32 v[70:71], v[72:73], v[124:125], v[156:157]
	v_mul_f32_e32 v199, v162, v78
	v_pk_fma_f32 v[80:81], v[74:75], v[148:149], v[70:71] op_sel_hi:[0,1,1]
	v_mul_f32_e32 v74, v172, v78
	v_fmac_f32_e32 v74, v79, v173
	v_fmac_f32_e32 v74, v80, v174
	v_fmac_f32_e32 v74, v81, v175
	ds_read_b128 v[70:73], v56 offset:6912
	v_fmac_f32_e32 v199, v79, v163
	v_add_f32_dpp v74, v74, v74 row_ror:8 row_mask:0xf bank_mask:0xf bound_ctrl:1
	v_fmac_f32_e32 v199, v80, v164
	v_pk_fma_f32 v[190:191], v[78:79], v[26:27], v[102:103]
	v_add_f32_dpp v74, v74, v74 row_ror:4 row_mask:0xf bank_mask:0xf bound_ctrl:1
	v_pk_mul_f32 v[26:27], v[184:185], v[46:47] op_sel_hi:[1,0]
	v_fmac_f32_e32 v199, v81, v165
	v_add_f32_dpp v74, v74, v74 row_ror:2 row_mask:0xf bank_mask:0xf bound_ctrl:1
	v_pk_fma_f32 v[192:193], v[80:81], v[28:29], v[26:27]
	v_mov_b32_e32 v46, v47
	v_add_f32_dpp v130, v74, v74 row_ror:1 row_mask:0xf bank_mask:0xf bound_ctrl:1
	ds_read_b128 v[74:77], v56 offset:2816
	ds_read_b128 v[26:29], v56 offset:10752
	ds_read_b128 v[78:81], v56 offset:11008
	ds_read_b128 v[82:85], v56 offset:18944
	ds_read_b128 v[86:89], v56 offset:19200
	ds_read2_b32 v[194:195], v45 offset0:192 offset1:208
	ds_read_b128 v[90:93], v56 offset:3072
	ds_read_b128 v[94:97], v56 offset:3328
	ds_read_b128 v[98:101], v56 offset:7168
	ds_read_b128 v[102:105], v56 offset:7424
	ds_read_b128 v[106:109], v56 offset:11264
	ds_read_b128 v[110:113], v56 offset:11520
	ds_read_b128 v[114:117], v56 offset:15360
	ds_read_b128 v[118:121], v56 offset:15616
	ds_read_b128 v[122:125], v56 offset:19456
	ds_read_b128 v[126:129], v56 offset:19712
	ds_read2_b32 v[196:197], v45 offset0:224 offset1:240
	ds_read_b128 v[138:141], v56 offset:3584
	ds_read_b128 v[142:145], v56 offset:3840
	ds_read_b128 v[146:149], v56 offset:7680
	ds_read_b128 v[150:153], v56 offset:7936
	ds_read_b128 v[154:157], v56 offset:11776
	ds_read_b128 v[158:161], v56 offset:12032
	ds_read_b128 v[162:165], v56 offset:15872
	ds_read_b128 v[172:175], v56 offset:16128
	ds_read_b128 v[182:185], v56 offset:19968
	ds_read_b128 v[186:189], v56 offset:20224
	s_waitcnt lgkmcnt(0)
	v_pk_fma_f32 v[26:27], v[130:131], v[26:27], v[190:191] op_sel_hi:[0,1,1]
	v_mul_f32_e32 v190, v70, v26
	v_fmac_f32_e32 v190, v27, v71
	v_pk_fma_f32 v[28:29], v[130:131], v[28:29], v[192:193] op_sel_hi:[0,1,1]
	v_mul_f32_e32 v45, v82, v26
	v_fmac_f32_e32 v190, v28, v72
	v_fmac_f32_e32 v45, v27, v83
	v_pk_mul_f32 v[66:67], v[66:67], v[46:47] op_sel_hi:[1,0]
	v_pk_mul_f32 v[46:47], v[68:69], v[46:47] op_sel_hi:[1,0]
	v_fmac_f32_e32 v190, v29, v73
	v_pk_fma_f32 v[46:47], v[28:29], v[76:77], v[46:47]
	v_fmac_f32_e32 v45, v28, v84
	v_add_f32_dpp v28, v190, v190 row_ror:8 row_mask:0xf bank_mask:0xf bound_ctrl:1
	v_pk_fma_f32 v[26:27], v[26:27], v[74:75], v[66:67]
	v_fmac_f32_e32 v45, v29, v85
	v_add_f32_dpp v28, v28, v28 row_ror:4 row_mask:0xf bank_mask:0xf bound_ctrl:1
	v_pk_mul_f32 v[66:67], v[114:115], v[194:195] op_sel_hi:[1,0]
	v_pk_mul_f32 v[68:69], v[116:117], v[194:195] op_sel_hi:[1,0]
	v_add_f32_dpp v28, v28, v28 row_ror:2 row_mask:0xf bank_mask:0xf bound_ctrl:1
	v_mov_b32_e32 v70, v195
	v_pk_mul_f32 v[74:75], v[118:119], v[70:71] op_sel_hi:[1,0]
	v_add_f32_dpp v28, v28, v28 row_ror:1 row_mask:0xf bank_mask:0xf bound_ctrl:1
	v_pk_fma_f32 v[26:27], v[28:29], v[78:79], v[26:27] op_sel_hi:[0,1,1]
	v_pk_fma_f32 v[28:29], v[28:29], v[80:81], v[46:47] op_sel_hi:[0,1,1]
	v_mul_f32_e32 v46, v98, v26
	v_fmac_f32_e32 v46, v27, v99
	v_fmac_f32_e32 v46, v28, v100
	v_fmac_f32_e32 v46, v29, v101
	v_mul_f32_e32 v47, v86, v26
	v_fmac_f32_e32 v47, v27, v87
	v_add_f32_dpp v46, v46, v46 row_ror:8 row_mask:0xf bank_mask:0xf bound_ctrl:1
	v_fmac_f32_e32 v47, v28, v88
	v_fmac_f32_e32 v47, v29, v89
	v_add_f32_dpp v46, v46, v46 row_ror:4 row_mask:0xf bank_mask:0xf bound_ctrl:1
	v_pk_fma_f32 v[26:27], v[26:27], v[90:91], v[66:67]
	v_pk_fma_f32 v[28:29], v[28:29], v[92:93], v[68:69]
	v_add_f32_dpp v46, v46, v46 row_ror:2 row_mask:0xf bank_mask:0xf bound_ctrl:1
	v_pk_mul_f32 v[70:71], v[120:121], v[70:71] op_sel_hi:[1,0]
	v_pk_mul_f32 v[82:83], v[162:163], v[196:197] op_sel_hi:[1,0]
	v_add_f32_dpp v46, v46, v46 row_ror:1 row_mask:0xf bank_mask:0xf bound_ctrl:1
	v_pk_fma_f32 v[26:27], v[46:47], v[106:107], v[26:27] op_sel_hi:[0,1,1]
	v_pk_fma_f32 v[28:29], v[46:47], v[108:109], v[28:29] op_sel_hi:[0,1,1]
	v_mul_f32_e32 v46, v102, v26
	v_fmac_f32_e32 v46, v27, v103
	v_fmac_f32_e32 v46, v28, v104
	v_fmac_f32_e32 v46, v29, v105
	v_mul_f32_e32 v68, v122, v26
	v_fmac_f32_e32 v68, v27, v123
	v_add_f32_dpp v46, v46, v46 row_ror:8 row_mask:0xf bank_mask:0xf bound_ctrl:1
	v_fmac_f32_e32 v68, v28, v124
	v_pk_fma_f32 v[26:27], v[26:27], v[94:95], v[74:75]
	v_add_f32_dpp v46, v46, v46 row_ror:4 row_mask:0xf bank_mask:0xf bound_ctrl:1
	v_fmac_f32_e32 v68, v29, v125
	v_pk_fma_f32 v[28:29], v[28:29], v[96:97], v[70:71]
	v_add_f32_dpp v46, v46, v46 row_ror:2 row_mask:0xf bank_mask:0xf bound_ctrl:1
	v_pk_mul_f32 v[76:77], v[164:165], v[196:197] op_sel_hi:[1,0]
	v_mov_b32_e32 v114, v197
	v_add_f32_dpp v46, v46, v46 row_ror:1 row_mask:0xf bank_mask:0xf bound_ctrl:1
; template <int CTRL> DI float dpp_get(float x) { return __int_as_float(__builtin_amdgcn_update_dpp(0, __float_as_int(x), CTRL, 0xf, 0xf, false)); }
; DI void scan_chunk(const float* buf, f32x4& S, int w, int rw, int kg, float& ys) {
;     ...
;   const bool b3 = (kg & 8) != 0, b2 = (kg & 4) != 0, b1 = (kg & 2) != 0, b0 = (kg & 1) != 0;
;   float t[8], u[4], v2[2];
; #pragma unroll
;   for (int j = 0; j < 8; ++j) { float keep = b3 ? yp[j + 8] : yp[j], send = b3 ? yp[j] : yp[j + 8]; t[j] = keep + dpp_get<0x140>(send); }
; #pragma unroll
;   for (int j = 0; j < 4; ++j) { float keep = b2 ? t[j + 4] : t[j], send = b2 ? t[j] : t[j + 4]; u[j] = keep + dpp_get<0x141>(send); }
; #pragma unroll
;   for (int j = 0; j < 2; ++j) { float keep = b1 ? u[j + 2] : u[j], send = b1 ? u[j] : u[j + 2]; v2[j] = keep + dpp_get<0x4E>(send); }
;   { float keep = b0 ? v2[1] : v2[0], send = b0 ? v2[0] : v2[1]; ys = keep + dpp_get<0xB1>(send); }
; DI void scan_job(const int tid_, const Params& p, int l, int job, char* s0, char* s1, char* s2) {
;     ...
;       Y[(size_t)(tok0 + (c + 1) * 16 + kg) * 512 + h * 64 + row] = ys;
;       if (c + 2 < nchunks) scan_lstore(tid_, B, buf0);
	v_pk_fma_f32 v[26:27], v[46:47], v[110:111], v[26:27] op_sel_hi:[0,1,1]
	v_pk_fma_f32 v[28:29], v[46:47], v[112:113], v[28:29] op_sel_hi:[0,1,1]
	v_mul_f32_e32 v46, v146, v26
	v_fmac_f32_e32 v46, v27, v147
	v_fmac_f32_e32 v46, v28, v148
	v_fmac_f32_e32 v46, v29, v149
	v_mul_f32_e32 v69, v126, v26
	v_fmac_f32_e32 v69, v27, v127
	v_add_f32_dpp v46, v46, v46 row_ror:8 row_mask:0xf bank_mask:0xf bound_ctrl:1
	v_fmac_f32_e32 v69, v28, v128
	v_pk_fma_f32 v[26:27], v[26:27], v[138:139], v[82:83]
	v_add_f32_dpp v46, v46, v46 row_ror:4 row_mask:0xf bank_mask:0xf bound_ctrl:1
	v_fmac_f32_e32 v69, v29, v129
	v_pk_fma_f32 v[28:29], v[28:29], v[140:141], v[76:77]
	v_add_f32_dpp v46, v46, v46 row_ror:2 row_mask:0xf bank_mask:0xf bound_ctrl:1
	v_pk_mul_f32 v[118:119], v[172:173], v[114:115] op_sel_hi:[1,0]
	v_pk_mul_f32 v[66:67], v[174:175], v[114:115] op_sel_hi:[1,0]
	v_add_f32_dpp v46, v46, v46 row_ror:1 row_mask:0xf bank_mask:0xf bound_ctrl:1
	v_pk_fma_f32 v[26:27], v[46:47], v[154:155], v[26:27] op_sel_hi:[0,1,1]
	v_pk_fma_f32 v[28:29], v[46:47], v[156:157], v[28:29] op_sel_hi:[0,1,1]
	v_mul_f32_e32 v46, v150, v26
	v_fmac_f32_e32 v46, v27, v151
	v_fmac_f32_e32 v46, v28, v152
	v_fmac_f32_e32 v46, v29, v153
	v_mul_f32_e32 v70, v182, v26
	v_fmac_f32_e32 v70, v27, v183
	v_add_f32_dpp v46, v46, v46 row_ror:8 row_mask:0xf bank_mask:0xf bound_ctrl:1
	v_fmac_f32_e32 v70, v28, v184
	v_fmac_f32_e32 v70, v29, v185
	v_add_f32_dpp v46, v46, v46 row_ror:4 row_mask:0xf bank_mask:0xf bound_ctrl:1
	v_pk_fma_f32 v[26:27], v[26:27], v[142:143], v[118:119]
	v_pk_fma_f32 v[28:29], v[28:29], v[144:145], v[66:67]
	v_add_f32_dpp v46, v46, v46 row_ror:2 row_mask:0xf bank_mask:0xf bound_ctrl:1
	v_cndmask_b32_e64 v66, v198, v0, s[40:41]
	v_cndmask_b32_e64 v0, v0, v198, s[40:41]
	v_add_f32_dpp v46, v46, v46 row_ror:1 row_mask:0xf bank_mask:0xf bound_ctrl:1
	v_pk_fma_f32 v[26:27], v[46:47], v[158:159], v[26:27] op_sel_hi:[0,1,1]
	v_add_f32_dpp v0, v0, v66 row_mirror row_mask:0xf bank_mask:0xf bound_ctrl:1
	v_cndmask_b32_e64 v66, v199, v62, s[40:41]
	v_cndmask_b32_e64 v62, v62, v199, s[40:41]
	v_pk_fma_f32 v[28:29], v[46:47], v[160:161], v[28:29] op_sel_hi:[0,1,1]
	v_mul_f32_e32 v46, v186, v26
	v_add_f32_dpp v62, v62, v66 row_mirror row_mask:0xf bank_mask:0xf bound_ctrl:1
	v_cndmask_b32_e64 v66, v45, v63, s[40:41]
	v_cndmask_b32_e64 v45, v63, v45, s[40:41]
	v_cndmask_b32_e64 v63, v47, v64, s[40:41]
	v_cndmask_b32_e64 v47, v64, v47, s[40:41]
	v_fmac_f32_e32 v46, v27, v187
	v_cndmask_b32_e64 v64, v65, v68, s[40:41]
	v_add_f32_dpp v47, v47, v63 row_mirror row_mask:0xf bank_mask:0xf bound_ctrl:1
	v_cndmask_b32_e64 v63, v68, v65, s[40:41]
	v_fmac_f32_e32 v46, v28, v188
	v_cndmask_b32_e64 v65, v131, v69, s[40:41]
	v_add_f32_dpp v63, v64, v63 row_mirror row_mask:0xf bank_mask:0xf bound_ctrl:1
	v_cndmask_b32_e64 v64, v69, v131, s[40:41]
	v_fmac_f32_e32 v46, v29, v189
	v_add_f32_dpp v45, v45, v66 row_mirror row_mask:0xf bank_mask:0xf bound_ctrl:1
	v_add_f32_dpp v64, v65, v64 row_mirror row_mask:0xf bank_mask:0xf bound_ctrl:1
	v_cndmask_b32_e64 v65, v70, v135, s[40:41]
	v_cndmask_b32_e64 v66, v135, v70, s[40:41]
	s_nop 1
	v_add_f32_dpp v65, v66, v65 row_mirror row_mask:0xf bank_mask:0xf bound_ctrl:1
	v_cndmask_b32_e64 v66, v46, v181, s[40:41]
	v_cndmask_b32_e64 v46, v181, v46, s[40:41]
	s_nop 1
	v_add_f32_dpp v46, v46, v66 row_mirror row_mask:0xf bank_mask:0xf bound_ctrl:1
	v_cndmask_b32_e64 v66, v63, v0, s[42:43]
	v_cndmask_b32_e64 v0, v0, v63, s[42:43]
	v_cndmask_b32_e64 v63, v64, v62, s[42:43]
	v_cndmask_b32_e64 v62, v62, v64, s[42:43]
	v_add_f32_dpp v0, v0, v66 row_half_mirror row_mask:0xf bank_mask:0xf bound_ctrl:1
	s_nop 0
	v_add_f32_dpp v62, v62, v63 row_half_mirror row_mask:0xf bank_mask:0xf bound_ctrl:1
	v_cndmask_b32_e64 v63, v65, v45, s[42:43]
	v_cndmask_b32_e64 v45, v45, v65, s[42:43]
	s_nop 1
	v_add_f32_dpp v45, v45, v63 row_half_mirror row_mask:0xf bank_mask:0xf bound_ctrl:1
	v_cndmask_b32_e64 v63, v46, v47, s[42:43]
	v_cndmask_b32_e64 v46, v47, v46, s[42:43]
	v_cndmask_b32_e64 v47, v45, v0, s[44:45]
	v_cndmask_b32_e64 v0, v0, v45, s[44:45]
	v_add_f32_dpp v46, v46, v63 row_half_mirror row_mask:0xf bank_mask:0xf bound_ctrl:1
	v_cndmask_b32_e64 v45, v46, v62, s[44:45]
	v_cndmask_b32_e64 v46, v62, v46, s[44:45]
	v_add_f32_dpp v0, v0, v47 quad_perm:[2,3,0,1] row_mask:0xf bank_mask:0xf bound_ctrl:1
	s_nop 0
	v_add_f32_dpp v45, v46, v45 quad_perm:[2,3,0,1] row_mask:0xf bank_mask:0xf bound_ctrl:1
	v_cndmask_b32_e64 v46, v45, v0, s[46:47]
	v_cndmask_b32_e64 v0, v0, v45, s[46:47]
	s_nop 1
	v_add_f32_dpp v46, v0, v46 quad_perm:[1,0,3,2] row_mask:0xf bank_mask:0xf bound_ctrl:1
	v_add_u32_e32 v0, 16, v44
	v_lshlrev_b64 v[44:45], 11, v[0:1]
	v_lshl_add_u64 v[44:45], v[36:37], 0, v[44:45]
	flat_store_dword v[44:45], v46
	s_cbranch_vccnz .LBB0_182
	s_waitcnt vmcnt(1)
	v_lshlrev_b32_e32 v0, 16, v61
	v_lshlrev_b32_e32 v44, 16, v18
	v_and_b32_e32 v45, 0xffff0000, v18
	v_lshlrev_b32_e32 v46, 16, v19
	v_and_b32_e32 v47, 0xffff0000, v19
	ds_write_b128 v52, v[14:17]
	ds_write_b32 v53, v0 offset:20480
	ds_write_b128 v54, v[44:47] offset:4096
	v_lshlrev_b32_e32 v44, 16, v20
	v_and_b32_e32 v45, 0xffff0000, v20
	v_lshlrev_b32_e32 v46, 16, v21
	v_and_b32_e32 v47, 0xffff0000, v21
	ds_write_b128 v54, v[44:47] offset:4112
	v_lshlrev_b32_e32 v44, 16, v22
	v_and_b32_e32 v45, 0xffff0000, v22
	v_lshlrev_b32_e32 v46, 16, v23
	v_and_b32_e32 v47, 0xffff0000, v23
	ds_write_b128 v54, v[44:47] offset:12288
	v_lshlrev_b32_e32 v44, 16, v24
	v_and_b32_e32 v45, 0xffff0000, v24
	v_lshlrev_b32_e32 v46, 16, v25
	v_and_b32_e32 v47, 0xffff0000, v25
	ds_write_b128 v54, v[44:47] offset:12304
	s_branch .LBB0_182
